# same as previous version plus a 2-wait-state pad before the last v_cndmask of the row select (v_cmp -> mask read hazard margin)
# speedup vs baseline: 1.0043x; 1.0004x over previous
; #define LAS __attribute__((address_space(3)))
; __device__ __forceinline__ int crow(int r, int hi) { return (r & 3) + 8 * (r >> 2) + 4 * hi; }
; __device__ __forceinline__ void attn_unit(LAS unsigned char* lds, bf16_t* Zg, const unsigned char* KVg, int S, int b, int h, int qb, const float* lq1, const float* lk1, const float* lq2, const float* lk2, const float* subln_g, const float* rel_bias, bool dostore = true) {
;     ...
;     for (int g = 0; g < 4; ++g) { const f32x4 a4 = *(const LAS f32x4*)(wsf + 8 * g + 4 * hi); inv[4 * g] = a4.x; inv[4 * g + 1] = a4.y; inv[4 * g + 2] = a4.z; inv[4 * g + 3] = a4.w; }
;     LAS float* exch = (LAS float*)lds;
;     if (mp == 1) {
; #pragma unroll
;         for (int db = 0; db < 4; ++db)
; #pragma unroll
;             for (int r = 0; r < 16; ++r) exch[(32 * qsub + crow(r, hi)) * 128 + db * 32 + r32] = o[db][r] * inv[r];
;     }
;     __syncthreads();
;     if (mp == 0) {
;         float ss[16];
; #pragma unroll
;         for (int r = 0; r < 16; ++r) { float a = 0.f;
; #pragma unroll
;             for (int db = 0; db < 4; ++db) { const float d = o[db][r] * inv[r] - exch[(32 * qsub + crow(r, hi)) * 128 + db * 32 + r32]; o[db][r] = d; a += d * d; }
;             ss[r] = a; }
.LBB0_285:
	s_or_b64 exec, exec, s[6:7]
	s_waitcnt lgkmcnt(0)
	ds_read_b128 v[78:81], v212
	ds_read_b128 v[74:77], v212 offset:32
	s_waitcnt lgkmcnt(2)
	ds_read_b128 v[70:73], v212 offset:64
	ds_read_b128 v[66:69], v212 offset:96
	s_cmp_lg_u32 s89, 1
	v_lshlrev_b32_e32 v82, 2, v210
	s_cbranch_scc1 .Lcmb_map0
	v_or_b32_e32 v0, s85, v211
	v_lshlrev_b32_e32 v0, 9, v0
	v_add3_u32 v0, 0, v82, v0
	global_load_dword v190, v82, s[68:69]
	global_load_dword v191, v82, s[68:69] offset:128
	global_load_dword v192, v82, s[68:69] offset:256
	global_load_dword v193, v82, s[68:69] offset:384
	v_add_u32_e32 v105, 0x400, v0
	v_add_u32_e32 v106, 0x1000, v0
	v_add_u32_e32 v107, 0x1400, v0
	v_add_u32_e32 v108, 0x2000, v0
	v_add_u32_e32 v109, 0x2400, v0
	v_add_u32_e32 v110, 0x3000, v0
	v_add_u32_e32 v111, 0x3400, v0
	s_waitcnt lgkmcnt(0)
	v_mul_f32_e32 v89, v50, v78
	v_mul_f32_e32 v90, v34, v78
	ds_write2_b32 v0, v89, v90 offset1:32
	v_mul_f32_e32 v91, v18, v78
	v_mul_f32_e32 v92, v2, v78
	ds_write2_b32 v0, v91, v92 offset0:64 offset1:96
	v_mul_f32_e32 v93, v51, v79
	v_mul_f32_e32 v94, v35, v79
	ds_write2_b32 v0, v93, v94 offset0:128 offset1:160
	v_mul_f32_e32 v95, v19, v79
	v_mul_f32_e32 v96, v3, v79
	ds_write2_b32 v0, v95, v96 offset0:192 offset1:224
	v_mul_f32_e32 v97, v52, v80
	v_mul_f32_e32 v98, v36, v80
	ds_write2_b32 v105, v97, v98 offset1:32
	v_mul_f32_e32 v99, v20, v80
	v_mul_f32_e32 v100, v4, v80
	ds_write2_b32 v105, v99, v100 offset0:64 offset1:96
	v_mul_f32_e32 v101, v53, v81
	v_mul_f32_e32 v102, v37, v81
	ds_write2_b32 v105, v101, v102 offset0:128 offset1:160
	v_mul_f32_e32 v103, v21, v81
	v_mul_f32_e32 v104, v5, v81
	ds_write2_b32 v105, v103, v104 offset0:192 offset1:224
	v_mul_f32_e32 v89, v54, v74
	v_mul_f32_e32 v90, v38, v74
	ds_write2_b32 v106, v89, v90 offset1:32
	v_mul_f32_e32 v91, v22, v74
	v_mul_f32_e32 v92, v6, v74
	ds_write2_b32 v106, v91, v92 offset0:64 offset1:96
	v_mul_f32_e32 v93, v55, v75
	v_mul_f32_e32 v94, v39, v75
	ds_write2_b32 v106, v93, v94 offset0:128 offset1:160
	v_mul_f32_e32 v95, v23, v75
	v_mul_f32_e32 v96, v7, v75
	ds_write2_b32 v106, v95, v96 offset0:192 offset1:224
	v_mul_f32_e32 v97, v56, v76
	v_mul_f32_e32 v98, v40, v76
	ds_write2_b32 v107, v97, v98 offset1:32
	v_mul_f32_e32 v99, v24, v76
	v_mul_f32_e32 v100, v8, v76
	ds_write2_b32 v107, v99, v100 offset0:64 offset1:96
	v_mul_f32_e32 v101, v57, v77
	v_mul_f32_e32 v102, v41, v77
	ds_write2_b32 v107, v101, v102 offset0:128 offset1:160
	v_mul_f32_e32 v103, v25, v77
	v_mul_f32_e32 v104, v9, v77
	ds_write2_b32 v107, v103, v104 offset0:192 offset1:224
	s_waitcnt lgkmcnt(0)
	s_barrier
	ds_read2_b32 v[178:179], v108 offset1:32
	ds_read2_b32 v[180:181], v108 offset0:64 offset1:96
	ds_read2_b32 v[182:183], v108 offset0:128 offset1:160
	ds_read2_b32 v[184:185], v108 offset0:192 offset1:224
	ds_read2_b32 v[186:187], v109 offset1:32
	ds_read2_b32 v[188:189], v109 offset0:64 offset1:96
	s_waitcnt lgkmcnt(5)
	v_fma_f32 v58, -v58, v70, v178
	v_fma_f32 v42, -v42, v70, v179
	ds_read2_b32 v[178:179], v109 offset0:128 offset1:160
	s_waitcnt lgkmcnt(5)
	v_fma_f32 v26, -v26, v70, v180
	v_fma_f32 v10, -v10, v70, v181
	ds_read2_b32 v[180:181], v109 offset0:192 offset1:224
	v_mul_f32_e32 v89, v42, v42
	v_fmac_f32_e32 v89, v58, v58
	v_fmac_f32_e32 v89, v26, v26
	v_fmac_f32_e32 v89, v10, v10
	s_waitcnt lgkmcnt(5)
	v_fma_f32 v59, -v59, v71, v182
	v_fma_f32 v43, -v43, v71, v183
	ds_read2_b32 v[182:183], v110 offset1:32
	s_waitcnt lgkmcnt(5)
	v_fma_f32 v27, -v27, v71, v184
	v_fma_f32 v11, -v11, v71, v185
	ds_read2_b32 v[184:185], v110 offset0:64 offset1:96
	v_mul_f32_e32 v90, v43, v43
	v_fmac_f32_e32 v90, v59, v59
	v_fmac_f32_e32 v90, v27, v27
	v_fmac_f32_e32 v90, v11, v11
	s_waitcnt lgkmcnt(5)
	v_fma_f32 v60, -v60, v72, v186
	v_fma_f32 v44, -v44, v72, v187
	ds_read2_b32 v[186:187], v110 offset0:128 offset1:160
	s_waitcnt lgkmcnt(5)
	v_fma_f32 v28, -v28, v72, v188
	v_fma_f32 v12, -v12, v72, v189
	ds_read2_b32 v[188:189], v110 offset0:192 offset1:224
	v_mul_f32_e32 v91, v44, v44
	v_fmac_f32_e32 v91, v60, v60
	v_fmac_f32_e32 v91, v28, v28
	v_fmac_f32_e32 v91, v12, v12
	s_waitcnt lgkmcnt(5)
	v_fma_f32 v61, -v61, v73, v178
	v_fma_f32 v45, -v45, v73, v179
	ds_read2_b32 v[178:179], v111 offset1:32
	s_waitcnt lgkmcnt(5)
	v_fma_f32 v29, -v29, v73, v180
	v_fma_f32 v13, -v13, v73, v181
	ds_read2_b32 v[180:181], v111 offset0:64 offset1:96
	v_mul_f32_e32 v92, v45, v45
	v_fmac_f32_e32 v92, v61, v61
	v_fmac_f32_e32 v92, v29, v29
	v_fmac_f32_e32 v92, v13, v13
	s_waitcnt lgkmcnt(5)
	v_fma_f32 v62, -v62, v66, v182
	v_fma_f32 v46, -v46, v66, v183
	ds_read2_b32 v[182:183], v111 offset0:128 offset1:160
	s_waitcnt lgkmcnt(5)
	v_fma_f32 v30, -v30, v66, v184
	v_fma_f32 v14, -v14, v66, v185
	ds_read2_b32 v[184:185], v111 offset0:192 offset1:224
	v_mul_f32_e32 v93, v46, v46
	v_fmac_f32_e32 v93, v62, v62
	v_fmac_f32_e32 v93, v30, v30
	v_fmac_f32_e32 v93, v14, v14
	s_waitcnt lgkmcnt(5)
	v_fma_f32 v63, -v63, v67, v186
	v_fma_f32 v47, -v47, v67, v187
	s_waitcnt lgkmcnt(4)
	v_fma_f32 v31, -v31, v67, v188
	v_fma_f32 v15, -v15, v67, v189
	v_mul_f32_e32 v94, v47, v47
	v_fmac_f32_e32 v94, v63, v63
	v_fmac_f32_e32 v94, v31, v31
	v_fmac_f32_e32 v94, v15, v15
	s_waitcnt lgkmcnt(3)
	v_fma_f32 v64, -v64, v68, v178
	v_fma_f32 v48, -v48, v68, v179
	s_waitcnt lgkmcnt(2)
	v_fma_f32 v32, -v32, v68, v180
	v_fma_f32 v16, -v16, v68, v181
	v_mul_f32_e32 v95, v48, v48
	v_fmac_f32_e32 v95, v64, v64
	v_fmac_f32_e32 v95, v32, v32
	v_fmac_f32_e32 v95, v16, v16
	s_waitcnt lgkmcnt(1)
	v_fma_f32 v65, -v65, v69, v182
	v_fma_f32 v49, -v49, v69, v183
	s_waitcnt lgkmcnt(0)
; __device__ __forceinline__ float shx(float v, int o, int lane) { return __int_as_float(__builtin_amdgcn_ds_bpermute((lane ^ o) << 2, __float_as_int(v))); }
; __device__ __forceinline__ void attn_unit(LAS unsigned char* lds, bf16_t* Zg, const unsigned char* KVg, int S, int b, int h, int qb, const float* lq1, const float* lk1, const float* lq2, const float* lk2, const float* subln_g, const float* rel_bias, bool dostore = true) {
;     ...
;         for (int r = 0; r < 16; ++r) {
; #pragma unroll
;             for (int sft = 1; sft < 32; sft <<= 1) ss[r] += shx(ss[r], sft, lane);
;             ss[r] = (1.0f - LAMBDA_INIT) / sqrtf(ss[r] * (1.0f / 128.0f) + EPS); }
	v_fma_f32 v33, -v33, v69, v184
	v_fma_f32 v17, -v17, v69, v185
	v_mul_f32_e32 v96, v49, v49
	v_fmac_f32_e32 v96, v65, v65
	v_fmac_f32_e32 v96, v33, v33
	v_fmac_f32_e32 v96, v17, v17
	s_nop 1
	v_mov_b32_dpp v84, v89 quad_perm:[1,0,3,2] row_mask:0xf bank_mask:0xf
	v_mov_b32_dpp v85, v90 quad_perm:[1,0,3,2] row_mask:0xf bank_mask:0xf
	v_mov_b32_dpp v86, v91 quad_perm:[1,0,3,2] row_mask:0xf bank_mask:0xf
	v_mov_b32_dpp v87, v92 quad_perm:[1,0,3,2] row_mask:0xf bank_mask:0xf
	v_add_f32_e32 v89, v89, v84
	v_add_f32_e32 v90, v90, v85
	v_add_f32_e32 v91, v91, v86
	v_add_f32_e32 v92, v92, v87
	v_mov_b32_dpp v84, v89 quad_perm:[2,3,0,1] row_mask:0xf bank_mask:0xf
	v_mov_b32_dpp v85, v90 quad_perm:[2,3,0,1] row_mask:0xf bank_mask:0xf
	v_mov_b32_dpp v86, v91 quad_perm:[2,3,0,1] row_mask:0xf bank_mask:0xf
	v_mov_b32_dpp v87, v92 quad_perm:[2,3,0,1] row_mask:0xf bank_mask:0xf
	v_add_f32_e32 v89, v89, v84
	v_add_f32_e32 v90, v90, v85
	v_add_f32_e32 v91, v91, v86
	v_add_f32_e32 v92, v92, v87
	v_mov_b32_dpp v84, v89 row_half_mirror row_mask:0xf bank_mask:0xf
	v_mov_b32_dpp v85, v90 row_half_mirror row_mask:0xf bank_mask:0xf
	v_mov_b32_dpp v86, v91 row_half_mirror row_mask:0xf bank_mask:0xf
	v_mov_b32_dpp v87, v92 row_half_mirror row_mask:0xf bank_mask:0xf
	v_add_f32_e32 v89, v89, v84
	v_add_f32_e32 v90, v90, v85
	v_add_f32_e32 v91, v91, v86
	v_add_f32_e32 v92, v92, v87
	v_mov_b32_dpp v84, v89 row_ror:8 row_mask:0xf bank_mask:0xf
	v_mov_b32_dpp v85, v90 row_ror:8 row_mask:0xf bank_mask:0xf
	v_mov_b32_dpp v86, v91 row_ror:8 row_mask:0xf bank_mask:0xf
	v_mov_b32_dpp v87, v92 row_ror:8 row_mask:0xf bank_mask:0xf
	v_add_f32_e32 v89, v89, v84
	v_add_f32_e32 v90, v90, v85
	v_add_f32_e32 v91, v91, v86
	v_add_f32_e32 v92, v92, v87
	v_mov_b32_e32 v84, v89
	v_mov_b32_e32 v85, v90
	v_mov_b32_e32 v86, v91
	v_mov_b32_e32 v87, v92
	v_permlane16_swap_b32_e32 v84, v89
	v_permlane16_swap_b32_e32 v85, v90
	v_permlane16_swap_b32_e32 v86, v91
	v_permlane16_swap_b32_e32 v87, v92
	v_add_f32_e32 v89, v89, v84
	v_add_f32_e32 v90, v90, v85
	v_add_f32_e32 v91, v91, v86
	v_add_f32_e32 v92, v92, v87
	s_nop 1
	v_mov_b32_dpp v84, v93 quad_perm:[1,0,3,2] row_mask:0xf bank_mask:0xf
	v_mov_b32_dpp v85, v94 quad_perm:[1,0,3,2] row_mask:0xf bank_mask:0xf
	v_mov_b32_dpp v86, v95 quad_perm:[1,0,3,2] row_mask:0xf bank_mask:0xf
	v_mov_b32_dpp v87, v96 quad_perm:[1,0,3,2] row_mask:0xf bank_mask:0xf
	v_add_f32_e32 v93, v93, v84
	v_add_f32_e32 v94, v94, v85
	v_add_f32_e32 v95, v95, v86
	v_add_f32_e32 v96, v96, v87
	v_mov_b32_dpp v84, v93 quad_perm:[2,3,0,1] row_mask:0xf bank_mask:0xf
	v_mov_b32_dpp v85, v94 quad_perm:[2,3,0,1] row_mask:0xf bank_mask:0xf
	v_mov_b32_dpp v86, v95 quad_perm:[2,3,0,1] row_mask:0xf bank_mask:0xf
	v_mov_b32_dpp v87, v96 quad_perm:[2,3,0,1] row_mask:0xf bank_mask:0xf
	v_add_f32_e32 v93, v93, v84
	v_add_f32_e32 v94, v94, v85
	v_add_f32_e32 v95, v95, v86
	v_add_f32_e32 v96, v96, v87
	v_mov_b32_dpp v84, v93 row_half_mirror row_mask:0xf bank_mask:0xf
	v_mov_b32_dpp v85, v94 row_half_mirror row_mask:0xf bank_mask:0xf
	v_mov_b32_dpp v86, v95 row_half_mirror row_mask:0xf bank_mask:0xf
	v_mov_b32_dpp v87, v96 row_half_mirror row_mask:0xf bank_mask:0xf
	v_add_f32_e32 v93, v93, v84
	v_add_f32_e32 v94, v94, v85
	v_add_f32_e32 v95, v95, v86
	v_add_f32_e32 v96, v96, v87
	v_mov_b32_dpp v84, v93 row_ror:8 row_mask:0xf bank_mask:0xf
	v_mov_b32_dpp v85, v94 row_ror:8 row_mask:0xf bank_mask:0xf
	v_mov_b32_dpp v86, v95 row_ror:8 row_mask:0xf bank_mask:0xf
	v_mov_b32_dpp v87, v96 row_ror:8 row_mask:0xf bank_mask:0xf
	v_add_f32_e32 v93, v93, v84
	v_add_f32_e32 v94, v94, v85
	v_add_f32_e32 v95, v95, v86
	v_add_f32_e32 v96, v96, v87
	v_mov_b32_e32 v84, v93
	v_mov_b32_e32 v85, v94
	v_mov_b32_e32 v86, v95
	v_mov_b32_e32 v87, v96
	v_permlane16_swap_b32_e32 v84, v93
	v_permlane16_swap_b32_e32 v85, v94
	v_permlane16_swap_b32_e32 v86, v95
	v_permlane16_swap_b32_e32 v87, v96
	v_add_f32_e32 v93, v93, v84
	v_add_f32_e32 v94, v94, v85
	v_add_f32_e32 v95, v95, v86
	v_add_f32_e32 v96, v96, v87
	v_bfe_u32 v86, v82, 2, 3
	v_mov_b32_e32 v88, v89
	v_cmp_eq_u32_e32 vcc, 1, v86
	v_cmp_eq_u32_e64 s[4:5], 2, v86
	s_nop 0
	v_cndmask_b32_e32 v88, v88, v90, vcc
	v_cndmask_b32_e64 v88, v88, v91, s[4:5]
	v_cmp_eq_u32_e32 vcc, 3, v86
	v_cmp_eq_u32_e64 s[4:5], 4, v86
	s_nop 0
	v_cndmask_b32_e32 v88, v88, v92, vcc
	v_cndmask_b32_e64 v88, v88, v93, s[4:5]
	v_cmp_eq_u32_e32 vcc, 5, v86
	v_cmp_eq_u32_e64 s[4:5], 6, v86
	s_nop 0
	v_cndmask_b32_e32 v88, v88, v94, vcc
	v_cndmask_b32_e64 v88, v88, v95, s[4:5]
	v_cmp_eq_u32_e32 vcc, 7, v86
	s_nop 1
	v_cndmask_b32_e32 v88, v88, v96, vcc
	v_fmamk_f32 v88, v88, 0x3c000000, v206
	v_cmp_gt_f32_e32 vcc, s36, v88
	v_mul_f32_e32 v178, 0x4f800000, v88
	s_nop 0
	v_cndmask_b32_e32 v88, v88, v178, vcc
	v_sqrt_f32_e32 v178, v88
	s_nop 0
	v_add_u32_e32 v179, -1, v178
	v_fma_f32 v180, -v179, v178, v88
	v_cmp_ge_f32_e64 s[4:5], 0, v180
	v_add_u32_e32 v180, 1, v178
	s_nop 0
	v_cndmask_b32_e64 v179, v178, v179, s[4:5]
	v_fma_f32 v178, -v180, v178, v88
	v_cmp_lt_f32_e64 s[4:5], 0, v178
	s_nop 1
	v_cndmask_b32_e64 v178, v179, v180, s[4:5]
	v_mul_f32_e32 v179, 0x37800000, v178
	v_cndmask_b32_e32 v178, v178, v179, vcc
	v_cmp_class_f32_e32 vcc, v88, v205
	s_nop 1
	v_cndmask_b32_e32 v88, v178, v88, vcc
	v_div_scale_f32 v178, s[4:5], v88, v88, s95
	v_rcp_f32_e32 v179, v178
	s_nop 0
	v_fma_f32 v180, -v178, v179, 1.0
	v_fmac_f32_e32 v179, v180, v179
	v_div_scale_f32 v180, vcc, s95, v88, s95
	v_mul_f32_e32 v181, v180, v179
	v_fma_f32 v182, -v178, v181, v180
	v_fmac_f32_e32 v181, v182, v179
	v_fma_f32 v178, -v178, v181, v180
	v_div_fmas_f32 v178, v178, v179, v181
	v_div_fixup_f32 v88, v178, v88, s95
	v_lshlrev_b32_e32 v84, 5, v211
	ds_bpermute_b32 v89, v84, v88
	ds_bpermute_b32 v90, v84, v88 offset:4
	ds_bpermute_b32 v91, v84, v88 offset:8
	ds_bpermute_b32 v92, v84, v88 offset:12
	ds_bpermute_b32 v93, v84, v88 offset:16
	ds_bpermute_b32 v94, v84, v88 offset:20
	ds_bpermute_b32 v95, v84, v88 offset:24
	ds_bpermute_b32 v96, v84, v88 offset:28
	s_waitcnt vmcnt(0) lgkmcnt(0)
; __device__ __forceinline__ int crow(int r, int hi) { return (r & 3) + 8 * (r >> 2) + 4 * hi; }
; __device__ __forceinline__ void attn_unit(LAS unsigned char* lds, bf16_t* Zg, const unsigned char* KVg, int S, int b, int h, int qb, const float* lq1, const float* lk1, const float* lq2, const float* lk2, const float* subln_g, const float* rel_bias, bool dostore = true) {
;     ...
;     if (mp == 1) {
; #pragma unroll
;         for (int db = 0; db < 4; ++db)
; #pragma unroll
;             for (int r = 0; r < 16; ++r) exch[(32 * qsub + crow(r, hi)) * 128 + db * 32 + r32] = o[db][r] * inv[r];
;     }
;     __syncthreads();
;     ...
;         for (int db = 0; db < 4; ++db) { const float sg = subln_g[db * 32 + r32];
; #pragma unroll
;             for (int r = 0; r < 16; ++r) exch[(32 * qsub + crow(r, hi)) * 128 + db * 32 + r32] = o[db][r] * ss[r] * sg; }
	v_mul_f32_e32 v58, v58, v89
	v_mul_f32_e32 v58, v58, v190
	v_mul_f32_e32 v42, v42, v89
	v_mul_f32_e32 v42, v42, v191
	ds_write2_b32 v108, v58, v42 offset1:32
	v_mul_f32_e32 v26, v26, v89
	v_mul_f32_e32 v26, v26, v192
	v_mul_f32_e32 v10, v10, v89
	v_mul_f32_e32 v10, v10, v193
	ds_write2_b32 v108, v26, v10 offset0:64 offset1:96
	v_mul_f32_e32 v59, v59, v90
	v_mul_f32_e32 v59, v59, v190
	v_mul_f32_e32 v43, v43, v90
	v_mul_f32_e32 v43, v43, v191
	ds_write2_b32 v108, v59, v43 offset0:128 offset1:160
	v_mul_f32_e32 v27, v27, v90
	v_mul_f32_e32 v27, v27, v192
	v_mul_f32_e32 v11, v11, v90
	v_mul_f32_e32 v11, v11, v193
	ds_write2_b32 v108, v27, v11 offset0:192 offset1:224
	v_mul_f32_e32 v60, v60, v91
	v_mul_f32_e32 v60, v60, v190
	v_mul_f32_e32 v44, v44, v91
	v_mul_f32_e32 v44, v44, v191
	ds_write2_b32 v109, v60, v44 offset1:32
	v_mul_f32_e32 v28, v28, v91
	v_mul_f32_e32 v28, v28, v192
	v_mul_f32_e32 v12, v12, v91
	v_mul_f32_e32 v12, v12, v193
	ds_write2_b32 v109, v28, v12 offset0:64 offset1:96
	v_mul_f32_e32 v61, v61, v92
	v_mul_f32_e32 v61, v61, v190
	v_mul_f32_e32 v45, v45, v92
	v_mul_f32_e32 v45, v45, v191
	ds_write2_b32 v109, v61, v45 offset0:128 offset1:160
	v_mul_f32_e32 v29, v29, v92
	v_mul_f32_e32 v29, v29, v192
	v_mul_f32_e32 v13, v13, v92
	v_mul_f32_e32 v13, v13, v193
	ds_write2_b32 v109, v29, v13 offset0:192 offset1:224
	v_mul_f32_e32 v62, v62, v93
	v_mul_f32_e32 v62, v62, v190
	v_mul_f32_e32 v46, v46, v93
	v_mul_f32_e32 v46, v46, v191
	ds_write2_b32 v110, v62, v46 offset1:32
	v_mul_f32_e32 v30, v30, v93
	v_mul_f32_e32 v30, v30, v192
	v_mul_f32_e32 v14, v14, v93
	v_mul_f32_e32 v14, v14, v193
	ds_write2_b32 v110, v30, v14 offset0:64 offset1:96
	v_mul_f32_e32 v63, v63, v94
	v_mul_f32_e32 v63, v63, v190
	v_mul_f32_e32 v47, v47, v94
	v_mul_f32_e32 v47, v47, v191
	ds_write2_b32 v110, v63, v47 offset0:128 offset1:160
	v_mul_f32_e32 v31, v31, v94
	v_mul_f32_e32 v31, v31, v192
	v_mul_f32_e32 v15, v15, v94
	v_mul_f32_e32 v15, v15, v193
	ds_write2_b32 v110, v31, v15 offset0:192 offset1:224
	v_mul_f32_e32 v64, v64, v95
	v_mul_f32_e32 v64, v64, v190
	v_mul_f32_e32 v48, v48, v95
	v_mul_f32_e32 v48, v48, v191
	ds_write2_b32 v111, v64, v48 offset1:32
	v_mul_f32_e32 v32, v32, v95
	v_mul_f32_e32 v32, v32, v192
	v_mul_f32_e32 v16, v16, v95
	v_mul_f32_e32 v16, v16, v193
	ds_write2_b32 v111, v32, v16 offset0:64 offset1:96
	v_mul_f32_e32 v65, v65, v96
	v_mul_f32_e32 v65, v65, v190
	v_mul_f32_e32 v49, v49, v96
	v_mul_f32_e32 v49, v49, v191
	ds_write2_b32 v111, v65, v49 offset0:128 offset1:160
	v_mul_f32_e32 v33, v33, v96
	v_mul_f32_e32 v33, v33, v192
	v_mul_f32_e32 v17, v17, v96
	v_mul_f32_e32 v17, v17, v193
	ds_write2_b32 v111, v33, v17 offset0:192 offset1:224
	s_branch .LBB0_187
.Lcmb_map0:
	v_or_b32_e32 v0, s84, v211
	v_lshlrev_b32_e32 v0, 9, v0
	v_add3_u32 v0, 0, v82, v0
	global_load_dword v190, v82, s[68:69]
	global_load_dword v191, v82, s[68:69] offset:128
	global_load_dword v192, v82, s[68:69] offset:256
	global_load_dword v193, v82, s[68:69] offset:384
	v_add_u32_e32 v105, 0x400, v0
	v_add_u32_e32 v106, 0x1000, v0
	v_add_u32_e32 v107, 0x1400, v0
	v_add_u32_e32 v108, 0x2000, v0
	v_add_u32_e32 v109, 0x2400, v0
	v_add_u32_e32 v110, 0x3000, v0
	v_add_u32_e32 v111, 0x3400, v0
	s_waitcnt lgkmcnt(0)
	v_mul_f32_e32 v89, v58, v70
	v_mul_f32_e32 v90, v42, v70
	ds_write2_b32 v108, v89, v90 offset1:32
	v_mul_f32_e32 v91, v26, v70
	v_mul_f32_e32 v92, v10, v70
	ds_write2_b32 v108, v91, v92 offset0:64 offset1:96
	v_mul_f32_e32 v93, v59, v71
	v_mul_f32_e32 v94, v43, v71
	ds_write2_b32 v108, v93, v94 offset0:128 offset1:160
	v_mul_f32_e32 v95, v27, v71
	v_mul_f32_e32 v96, v11, v71
	ds_write2_b32 v108, v95, v96 offset0:192 offset1:224
	v_mul_f32_e32 v97, v60, v72
	v_mul_f32_e32 v98, v44, v72
	ds_write2_b32 v109, v97, v98 offset1:32
	v_mul_f32_e32 v99, v28, v72
	v_mul_f32_e32 v100, v12, v72
	ds_write2_b32 v109, v99, v100 offset0:64 offset1:96
	v_mul_f32_e32 v101, v61, v73
	v_mul_f32_e32 v102, v45, v73
	ds_write2_b32 v109, v101, v102 offset0:128 offset1:160
	v_mul_f32_e32 v103, v29, v73
	v_mul_f32_e32 v104, v13, v73
	ds_write2_b32 v109, v103, v104 offset0:192 offset1:224
	v_mul_f32_e32 v89, v62, v66
	v_mul_f32_e32 v90, v46, v66
	ds_write2_b32 v110, v89, v90 offset1:32
	v_mul_f32_e32 v91, v30, v66
	v_mul_f32_e32 v92, v14, v66
	ds_write2_b32 v110, v91, v92 offset0:64 offset1:96
	v_mul_f32_e32 v93, v63, v67
	v_mul_f32_e32 v94, v47, v67
	ds_write2_b32 v110, v93, v94 offset0:128 offset1:160
	v_mul_f32_e32 v95, v31, v67
	v_mul_f32_e32 v96, v15, v67
	ds_write2_b32 v110, v95, v96 offset0:192 offset1:224
	v_mul_f32_e32 v97, v64, v68
	v_mul_f32_e32 v98, v48, v68
	ds_write2_b32 v111, v97, v98 offset1:32
	v_mul_f32_e32 v99, v32, v68
	v_mul_f32_e32 v100, v16, v68
	ds_write2_b32 v111, v99, v100 offset0:64 offset1:96
	v_mul_f32_e32 v101, v65, v69
	v_mul_f32_e32 v102, v49, v69
	ds_write2_b32 v111, v101, v102 offset0:128 offset1:160
	v_mul_f32_e32 v103, v33, v69
	v_mul_f32_e32 v104, v17, v69
	ds_write2_b32 v111, v103, v104 offset0:192 offset1:224
	s_waitcnt lgkmcnt(0)
	s_barrier
; __device__ __forceinline__ int crow(int r, int hi) { return (r & 3) + 8 * (r >> 2) + 4 * hi; }
; __device__ __forceinline__ void attn_unit(LAS unsigned char* lds, bf16_t* Zg, const unsigned char* KVg, int S, int b, int h, int qb, const float* lq1, const float* lk1, const float* lq2, const float* lk2, const float* subln_g, const float* rel_bias, bool dostore = true) {
;     ...
;     if (mp == 0) {
;         float ss[16];
; #pragma unroll
;         for (int r = 0; r < 16; ++r) { float a = 0.f;
; #pragma unroll
;             for (int db = 0; db < 4; ++db) { const float d = o[db][r] * inv[r] - exch[(32 * qsub + crow(r, hi)) * 128 + db * 32 + r32]; o[db][r] = d; a += d * d; }
;             ss[r] = a; }
	ds_read2_b32 v[178:179], v0 offset1:32
	ds_read2_b32 v[180:181], v0 offset0:64 offset1:96
	ds_read2_b32 v[182:183], v0 offset0:128 offset1:160
	ds_read2_b32 v[184:185], v0 offset0:192 offset1:224
	ds_read2_b32 v[186:187], v105 offset1:32
	ds_read2_b32 v[188:189], v105 offset0:64 offset1:96
	s_waitcnt lgkmcnt(5)
	v_fma_f32 v50, v50, v78, -v178
	v_fma_f32 v34, v34, v78, -v179
	ds_read2_b32 v[178:179], v105 offset0:128 offset1:160
	s_waitcnt lgkmcnt(5)
	v_fma_f32 v18, v18, v78, -v180
	v_fma_f32 v2, v2, v78, -v181
	ds_read2_b32 v[180:181], v105 offset0:192 offset1:224
	v_mul_f32_e32 v89, v34, v34
	v_fmac_f32_e32 v89, v50, v50
	v_fmac_f32_e32 v89, v18, v18
	v_fmac_f32_e32 v89, v2, v2
	s_waitcnt lgkmcnt(5)
	v_fma_f32 v51, v51, v79, -v182
	v_fma_f32 v35, v35, v79, -v183
	ds_read2_b32 v[182:183], v106 offset1:32
	s_waitcnt lgkmcnt(5)
	v_fma_f32 v19, v19, v79, -v184
	v_fma_f32 v3, v3, v79, -v185
	ds_read2_b32 v[184:185], v106 offset0:64 offset1:96
	v_mul_f32_e32 v90, v35, v35
	v_fmac_f32_e32 v90, v51, v51
	v_fmac_f32_e32 v90, v19, v19
	v_fmac_f32_e32 v90, v3, v3
	s_waitcnt lgkmcnt(5)
	v_fma_f32 v52, v52, v80, -v186
	v_fma_f32 v36, v36, v80, -v187
	ds_read2_b32 v[186:187], v106 offset0:128 offset1:160
	s_waitcnt lgkmcnt(5)
	v_fma_f32 v20, v20, v80, -v188
	v_fma_f32 v4, v4, v80, -v189
	ds_read2_b32 v[188:189], v106 offset0:192 offset1:224
	v_mul_f32_e32 v91, v36, v36
	v_fmac_f32_e32 v91, v52, v52
	v_fmac_f32_e32 v91, v20, v20
	v_fmac_f32_e32 v91, v4, v4
	s_waitcnt lgkmcnt(5)
	v_fma_f32 v53, v53, v81, -v178
	v_fma_f32 v37, v37, v81, -v179
	ds_read2_b32 v[178:179], v107 offset1:32
	s_waitcnt lgkmcnt(5)
	v_fma_f32 v21, v21, v81, -v180
	v_fma_f32 v5, v5, v81, -v181
	ds_read2_b32 v[180:181], v107 offset0:64 offset1:96
	v_mul_f32_e32 v92, v37, v37
	v_fmac_f32_e32 v92, v53, v53
	v_fmac_f32_e32 v92, v21, v21
	v_fmac_f32_e32 v92, v5, v5
	s_waitcnt lgkmcnt(5)
	v_fma_f32 v54, v54, v74, -v182
	v_fma_f32 v38, v38, v74, -v183
	ds_read2_b32 v[182:183], v107 offset0:128 offset1:160
	s_waitcnt lgkmcnt(5)
	v_fma_f32 v22, v22, v74, -v184
	v_fma_f32 v6, v6, v74, -v185
	ds_read2_b32 v[184:185], v107 offset0:192 offset1:224
	v_mul_f32_e32 v93, v38, v38
	v_fmac_f32_e32 v93, v54, v54
	v_fmac_f32_e32 v93, v22, v22
	v_fmac_f32_e32 v93, v6, v6
	s_waitcnt lgkmcnt(5)
	v_fma_f32 v55, v55, v75, -v186
	v_fma_f32 v39, v39, v75, -v187
	s_waitcnt lgkmcnt(4)
	v_fma_f32 v23, v23, v75, -v188
	v_fma_f32 v7, v7, v75, -v189
	v_mul_f32_e32 v94, v39, v39
	v_fmac_f32_e32 v94, v55, v55
	v_fmac_f32_e32 v94, v23, v23
	v_fmac_f32_e32 v94, v7, v7
	s_waitcnt lgkmcnt(3)
	v_fma_f32 v56, v56, v76, -v178
	v_fma_f32 v40, v40, v76, -v179
	s_waitcnt lgkmcnt(2)
	v_fma_f32 v24, v24, v76, -v180
	v_fma_f32 v8, v8, v76, -v181
	v_mul_f32_e32 v95, v40, v40
	v_fmac_f32_e32 v95, v56, v56
	v_fmac_f32_e32 v95, v24, v24
	v_fmac_f32_e32 v95, v8, v8
	s_waitcnt lgkmcnt(1)
	v_fma_f32 v57, v57, v77, -v182
	v_fma_f32 v41, v41, v77, -v183
	s_waitcnt lgkmcnt(0)
	v_fma_f32 v25, v25, v77, -v184
	v_fma_f32 v9, v9, v77, -v185
	v_mul_f32_e32 v96, v41, v41
	v_fmac_f32_e32 v96, v57, v57
	v_fmac_f32_e32 v96, v25, v25
	v_fmac_f32_e32 v96, v9, v9
	s_nop 1
	v_mov_b32_dpp v84, v89 quad_perm:[1,0,3,2] row_mask:0xf bank_mask:0xf
	v_mov_b32_dpp v85, v90 quad_perm:[1,0,3,2] row_mask:0xf bank_mask:0xf
	v_mov_b32_dpp v86, v91 quad_perm:[1,0,3,2] row_mask:0xf bank_mask:0xf
	v_mov_b32_dpp v87, v92 quad_perm:[1,0,3,2] row_mask:0xf bank_mask:0xf
	v_add_f32_e32 v89, v89, v84
	v_add_f32_e32 v90, v90, v85
	v_add_f32_e32 v91, v91, v86
	v_add_f32_e32 v92, v92, v87
	v_mov_b32_dpp v84, v89 quad_perm:[2,3,0,1] row_mask:0xf bank_mask:0xf
	v_mov_b32_dpp v85, v90 quad_perm:[2,3,0,1] row_mask:0xf bank_mask:0xf
	v_mov_b32_dpp v86, v91 quad_perm:[2,3,0,1] row_mask:0xf bank_mask:0xf
	v_mov_b32_dpp v87, v92 quad_perm:[2,3,0,1] row_mask:0xf bank_mask:0xf
	v_add_f32_e32 v89, v89, v84
	v_add_f32_e32 v90, v90, v85
	v_add_f32_e32 v91, v91, v86
	v_add_f32_e32 v92, v92, v87
	v_mov_b32_dpp v84, v89 row_half_mirror row_mask:0xf bank_mask:0xf
	v_mov_b32_dpp v85, v90 row_half_mirror row_mask:0xf bank_mask:0xf
	v_mov_b32_dpp v86, v91 row_half_mirror row_mask:0xf bank_mask:0xf
	v_mov_b32_dpp v87, v92 row_half_mirror row_mask:0xf bank_mask:0xf
	v_add_f32_e32 v89, v89, v84
	v_add_f32_e32 v90, v90, v85
	v_add_f32_e32 v91, v91, v86
	v_add_f32_e32 v92, v92, v87
	v_mov_b32_dpp v84, v89 row_ror:8 row_mask:0xf bank_mask:0xf
	v_mov_b32_dpp v85, v90 row_ror:8 row_mask:0xf bank_mask:0xf
	v_mov_b32_dpp v86, v91 row_ror:8 row_mask:0xf bank_mask:0xf
	v_mov_b32_dpp v87, v92 row_ror:8 row_mask:0xf bank_mask:0xf
	v_add_f32_e32 v89, v89, v84
	v_add_f32_e32 v90, v90, v85
	v_add_f32_e32 v91, v91, v86
	v_add_f32_e32 v92, v92, v87
	v_mov_b32_e32 v84, v89
	v_mov_b32_e32 v85, v90
	v_mov_b32_e32 v86, v91
	v_mov_b32_e32 v87, v92
	v_permlane16_swap_b32_e32 v84, v89
	v_permlane16_swap_b32_e32 v85, v90
	v_permlane16_swap_b32_e32 v86, v91
	v_permlane16_swap_b32_e32 v87, v92
	v_add_f32_e32 v89, v89, v84
	v_add_f32_e32 v90, v90, v85
	v_add_f32_e32 v91, v91, v86
	v_add_f32_e32 v92, v92, v87
	s_nop 1
	v_mov_b32_dpp v84, v93 quad_perm:[1,0,3,2] row_mask:0xf bank_mask:0xf
	v_mov_b32_dpp v85, v94 quad_perm:[1,0,3,2] row_mask:0xf bank_mask:0xf
	v_mov_b32_dpp v86, v95 quad_perm:[1,0,3,2] row_mask:0xf bank_mask:0xf
	v_mov_b32_dpp v87, v96 quad_perm:[1,0,3,2] row_mask:0xf bank_mask:0xf
	v_add_f32_e32 v93, v93, v84
	v_add_f32_e32 v94, v94, v85
	v_add_f32_e32 v95, v95, v86
	v_add_f32_e32 v96, v96, v87
	v_mov_b32_dpp v84, v93 quad_perm:[2,3,0,1] row_mask:0xf bank_mask:0xf
	v_mov_b32_dpp v85, v94 quad_perm:[2,3,0,1] row_mask:0xf bank_mask:0xf
	v_mov_b32_dpp v86, v95 quad_perm:[2,3,0,1] row_mask:0xf bank_mask:0xf
; __device__ __forceinline__ float shx(float v, int o, int lane) { return __int_as_float(__builtin_amdgcn_ds_bpermute((lane ^ o) << 2, __float_as_int(v))); }
; __device__ __forceinline__ int crow(int r, int hi) { return (r & 3) + 8 * (r >> 2) + 4 * hi; }
; __device__ __forceinline__ void attn_unit(LAS unsigned char* lds, bf16_t* Zg, const unsigned char* KVg, int S, int b, int h, int qb, const float* lq1, const float* lk1, const float* lq2, const float* lk2, const float* subln_g, const float* rel_bias, bool dostore = true) {
;     ...
;         for (int r = 0; r < 16; ++r) {
; #pragma unroll
;             for (int sft = 1; sft < 32; sft <<= 1) ss[r] += shx(ss[r], sft, lane);
;             ss[r] = (1.0f - LAMBDA_INIT) / sqrtf(ss[r] * (1.0f / 128.0f) + EPS); }
; #pragma unroll
;         for (int db = 0; db < 4; ++db) { const float sg = subln_g[db * 32 + r32];
; #pragma unroll
;             for (int r = 0; r < 16; ++r) exch[(32 * qsub + crow(r, hi)) * 128 + db * 32 + r32] = o[db][r] * ss[r] * sg; }
	v_mov_b32_dpp v87, v96 quad_perm:[2,3,0,1] row_mask:0xf bank_mask:0xf
	v_add_f32_e32 v93, v93, v84
	v_add_f32_e32 v94, v94, v85
	v_add_f32_e32 v95, v95, v86
	v_add_f32_e32 v96, v96, v87
	v_mov_b32_dpp v84, v93 row_half_mirror row_mask:0xf bank_mask:0xf
	v_mov_b32_dpp v85, v94 row_half_mirror row_mask:0xf bank_mask:0xf
	v_mov_b32_dpp v86, v95 row_half_mirror row_mask:0xf bank_mask:0xf
	v_mov_b32_dpp v87, v96 row_half_mirror row_mask:0xf bank_mask:0xf
	v_add_f32_e32 v93, v93, v84
	v_add_f32_e32 v94, v94, v85
	v_add_f32_e32 v95, v95, v86
	v_add_f32_e32 v96, v96, v87
	v_mov_b32_dpp v84, v93 row_ror:8 row_mask:0xf bank_mask:0xf
	v_mov_b32_dpp v85, v94 row_ror:8 row_mask:0xf bank_mask:0xf
	v_mov_b32_dpp v86, v95 row_ror:8 row_mask:0xf bank_mask:0xf
	v_mov_b32_dpp v87, v96 row_ror:8 row_mask:0xf bank_mask:0xf
	v_add_f32_e32 v93, v93, v84
	v_add_f32_e32 v94, v94, v85
	v_add_f32_e32 v95, v95, v86
	v_add_f32_e32 v96, v96, v87
	v_mov_b32_e32 v84, v93
	v_mov_b32_e32 v85, v94
	v_mov_b32_e32 v86, v95
	v_mov_b32_e32 v87, v96
	v_permlane16_swap_b32_e32 v84, v93
	v_permlane16_swap_b32_e32 v85, v94
	v_permlane16_swap_b32_e32 v86, v95
	v_permlane16_swap_b32_e32 v87, v96
	v_add_f32_e32 v93, v93, v84
	v_add_f32_e32 v94, v94, v85
	v_add_f32_e32 v95, v95, v86
	v_add_f32_e32 v96, v96, v87
	v_bfe_u32 v86, v82, 2, 3
	v_mov_b32_e32 v88, v89
	v_cmp_eq_u32_e32 vcc, 1, v86
	v_cmp_eq_u32_e64 s[4:5], 2, v86
	s_nop 0
	v_cndmask_b32_e32 v88, v88, v90, vcc
	v_cndmask_b32_e64 v88, v88, v91, s[4:5]
	v_cmp_eq_u32_e32 vcc, 3, v86
	v_cmp_eq_u32_e64 s[4:5], 4, v86
	s_nop 0
	v_cndmask_b32_e32 v88, v88, v92, vcc
	v_cndmask_b32_e64 v88, v88, v93, s[4:5]
	v_cmp_eq_u32_e32 vcc, 5, v86
	v_cmp_eq_u32_e64 s[4:5], 6, v86
	s_nop 0
	v_cndmask_b32_e32 v88, v88, v94, vcc
	v_cndmask_b32_e64 v88, v88, v95, s[4:5]
	v_cmp_eq_u32_e32 vcc, 7, v86
	s_nop 1
	v_cndmask_b32_e32 v88, v88, v96, vcc
	v_fmamk_f32 v88, v88, 0x3c000000, v206
	v_cmp_gt_f32_e32 vcc, s36, v88
	v_mul_f32_e32 v178, 0x4f800000, v88
	s_nop 0
	v_cndmask_b32_e32 v88, v88, v178, vcc
	v_sqrt_f32_e32 v178, v88
	s_nop 0
	v_add_u32_e32 v179, -1, v178
	v_fma_f32 v180, -v179, v178, v88
	v_cmp_ge_f32_e64 s[4:5], 0, v180
	v_add_u32_e32 v180, 1, v178
	s_nop 0
	v_cndmask_b32_e64 v179, v178, v179, s[4:5]
	v_fma_f32 v178, -v180, v178, v88
	v_cmp_lt_f32_e64 s[4:5], 0, v178
	s_nop 1
	v_cndmask_b32_e64 v178, v179, v180, s[4:5]
	v_mul_f32_e32 v179, 0x37800000, v178
	v_cndmask_b32_e32 v178, v178, v179, vcc
	v_cmp_class_f32_e32 vcc, v88, v205
	s_nop 1
	v_cndmask_b32_e32 v88, v178, v88, vcc
	v_div_scale_f32 v178, s[4:5], v88, v88, s95
	v_rcp_f32_e32 v179, v178
	s_nop 0
	v_fma_f32 v180, -v178, v179, 1.0
	v_fmac_f32_e32 v179, v180, v179
	v_div_scale_f32 v180, vcc, s95, v88, s95
	v_mul_f32_e32 v181, v180, v179
	v_fma_f32 v182, -v178, v181, v180
	v_fmac_f32_e32 v181, v182, v179
	v_fma_f32 v178, -v178, v181, v180
	v_div_fmas_f32 v178, v178, v179, v181
	v_div_fixup_f32 v88, v178, v88, s95
	v_lshlrev_b32_e32 v84, 5, v211
	ds_bpermute_b32 v89, v84, v88
	ds_bpermute_b32 v90, v84, v88 offset:4
	ds_bpermute_b32 v91, v84, v88 offset:8
	ds_bpermute_b32 v92, v84, v88 offset:12
	ds_bpermute_b32 v93, v84, v88 offset:16
	ds_bpermute_b32 v94, v84, v88 offset:20
	ds_bpermute_b32 v95, v84, v88 offset:24
	ds_bpermute_b32 v96, v84, v88 offset:28
	s_waitcnt vmcnt(0) lgkmcnt(0)
	v_mul_f32_e32 v50, v50, v89
	v_mul_f32_e32 v50, v50, v190
	v_mul_f32_e32 v34, v34, v89
	v_mul_f32_e32 v34, v34, v191
	ds_write2_b32 v0, v50, v34 offset1:32
	v_mul_f32_e32 v18, v18, v89
	v_mul_f32_e32 v18, v18, v192
	v_mul_f32_e32 v2, v2, v89
	v_mul_f32_e32 v2, v2, v193
	ds_write2_b32 v0, v18, v2 offset0:64 offset1:96
	v_mul_f32_e32 v51, v51, v90
	v_mul_f32_e32 v51, v51, v190
	v_mul_f32_e32 v35, v35, v90
	v_mul_f32_e32 v35, v35, v191
	ds_write2_b32 v0, v51, v35 offset0:128 offset1:160
	v_mul_f32_e32 v19, v19, v90
	v_mul_f32_e32 v19, v19, v192
	v_mul_f32_e32 v3, v3, v90
	v_mul_f32_e32 v3, v3, v193
	ds_write2_b32 v0, v19, v3 offset0:192 offset1:224
	v_mul_f32_e32 v52, v52, v91
	v_mul_f32_e32 v52, v52, v190
	v_mul_f32_e32 v36, v36, v91
	v_mul_f32_e32 v36, v36, v191
	ds_write2_b32 v105, v52, v36 offset1:32
	v_mul_f32_e32 v20, v20, v91
	v_mul_f32_e32 v20, v20, v192
	v_mul_f32_e32 v4, v4, v91
	v_mul_f32_e32 v4, v4, v193
	ds_write2_b32 v105, v20, v4 offset0:64 offset1:96
	v_mul_f32_e32 v53, v53, v92
	v_mul_f32_e32 v53, v53, v190
	v_mul_f32_e32 v37, v37, v92
	v_mul_f32_e32 v37, v37, v191
	ds_write2_b32 v105, v53, v37 offset0:128 offset1:160
	v_mul_f32_e32 v21, v21, v92
	v_mul_f32_e32 v21, v21, v192
	v_mul_f32_e32 v5, v5, v92
	v_mul_f32_e32 v5, v5, v193
	ds_write2_b32 v105, v21, v5 offset0:192 offset1:224
	v_mul_f32_e32 v54, v54, v93
	v_mul_f32_e32 v54, v54, v190
	v_mul_f32_e32 v38, v38, v93
	v_mul_f32_e32 v38, v38, v191
	ds_write2_b32 v106, v54, v38 offset1:32
	v_mul_f32_e32 v22, v22, v93
	v_mul_f32_e32 v22, v22, v192
	v_mul_f32_e32 v6, v6, v93
	v_mul_f32_e32 v6, v6, v193
	ds_write2_b32 v106, v22, v6 offset0:64 offset1:96
	v_mul_f32_e32 v55, v55, v94
	v_mul_f32_e32 v55, v55, v190
	v_mul_f32_e32 v39, v39, v94
	v_mul_f32_e32 v39, v39, v191
	ds_write2_b32 v106, v55, v39 offset0:128 offset1:160
	v_mul_f32_e32 v23, v23, v94
	v_mul_f32_e32 v23, v23, v192
	v_mul_f32_e32 v7, v7, v94
	v_mul_f32_e32 v7, v7, v193
	ds_write2_b32 v106, v23, v7 offset0:192 offset1:224
	v_mul_f32_e32 v56, v56, v95
	v_mul_f32_e32 v56, v56, v190
	v_mul_f32_e32 v40, v40, v95
	v_mul_f32_e32 v40, v40, v191
	ds_write2_b32 v107, v56, v40 offset1:32
	v_mul_f32_e32 v24, v24, v95
	v_mul_f32_e32 v24, v24, v192
	v_mul_f32_e32 v8, v8, v95
	v_mul_f32_e32 v8, v8, v193
	ds_write2_b32 v107, v24, v8 offset0:64 offset1:96
	v_mul_f32_e32 v57, v57, v96
	v_mul_f32_e32 v57, v57, v190
	v_mul_f32_e32 v41, v41, v96
	v_mul_f32_e32 v41, v41, v191
	ds_write2_b32 v107, v57, v41 offset0:128 offset1:160
	v_mul_f32_e32 v25, v25, v96
	v_mul_f32_e32 v25, v25, v192
	v_mul_f32_e32 v9, v9, v96
	v_mul_f32_e32 v9, v9, v193
	ds_write2_b32 v107, v25, v9 offset0:192 offset1:224
	s_branch .LBB0_187
